# layer-0 w_up/w_down conversions moved from prep phase to merge-phase slack of blocks 160-255 (second pass of the layer-1 conversion loop)
# baseline (speedup 1.0000x reference)
.LBB0_431:
	s_add_u32 s2, s72, 0x1180000
	s_addc_u32 s3, s73, 0
	s_cmp_eq_u32 s40, s2
	s_cbranch_scc1 .Llz_done
	s_mov_b64 s[40:41], s[2:3]
	s_add_u32 s8, s72, 0x1c80000
	s_addc_u32 s9, s73, 0
	v_readlane_b32 s18, v255, 16
	v_readlane_b32 s19, v255, 17
	v_readlane_b32 s0, v255, 18
	v_readlane_b32 s1, v255, 19
	v_readlane_b32 s7, v255, 22
	s_add_i32 s7, s7, 0x180
	s_branch .LBB0_414

.LBB0_1797:
	s_add_i32 s43, s40, s43
	s_cmpk_lg_i32 s89, 0x100
	s_cbranch_scc1 .Llz_b
	s_cmpk_gt_i32 s43, 0x2df
	s_cbranch_scc1 .LBB0_1829
